# RC1: next unit's r/k/v/a operand loads issued one unit ahead (S3 start) into spare VGPRs, copied at unit head
# speedup vs baseline: 1.0038x; 1.0038x over previous
.LBB0_1033:
	v_writelane_b32 v238, s87, 46
	v_writelane_b32 v238, s86, 47
	s_or_b64 exec, exec, s[0:1]
	s_add_u32 s0, s80, 0xa900000
	s_addc_u32 s1, s81, 0
	s_ashr_i32 s4, s40, 5
	s_ashr_i32 s5, s4, 31
	s_lshl_b64 s[52:53], s[4:5], 12
	s_lshl_b32 s2, s40, 6
	s_and_b32 s2, s2, 0xc0
	v_or_b32_e32 v92, s52, v176
	v_or_b32_e32 v4, s2, v92
	v_mov_b32_e32 v5, s53
	v_mov_b32_e32 v89, 0
	v_lshlrev_b64 v[4:5], 11, v[4:5]
	v_lshl_add_u64 v[4:5], s[0:1], 0, v[4:5]
	v_lshlrev_b64 v[10:11], 2, v[88:89]
	s_mov_b32 s55, 0
	v_and_b32_e32 v109, 0xffffffc0, v2
	v_lshl_add_u64 v[2:3], v[4:5], 0, v[10:11]
	s_lshl_b32 s54, s93, 5
	v_lshl_add_u64 v[12:13], v[2:3], 0, s[54:55]
	global_load_dwordx4 v[2:5], v[12:13], off offset:16
	global_load_dwordx4 v[6:9], v[12:13], off
	v_lshlrev_b32_e32 v12, 4, v178
	v_mov_b32_e32 v13, v89
	v_lshl_add_u64 v[14:15], v[88:89], 1, s[80:81]
	v_lshl_add_u64 v[12:13], v[14:15], 0, v[12:13]
	s_mov_b64 s[4:5], 0xe900000
	v_lshl_add_u64 v[94:95], v[12:13], 0, s[4:5]
	s_mov_b64 s[4:5], 0x8400000
	v_lshl_add_u64 v[96:97], v[12:13], 0, s[4:5]
	v_mbcnt_lo_u32_b32 v13, -1, 0
	v_mbcnt_hi_u32_b32 v13, -1, v13
	v_and_b32_e32 v15, 64, v13
	v_xor_b32_e32 v14, 1, v13
	v_add_u32_e32 v15, 64, v15
	v_and_b32_e32 v104, 15, v0
	v_cmp_lt_i32_e32 vcc, v14, v15
	v_lshl_add_u64 v[10:11], s[0:1], 0, v[10:11]
	v_cmp_eq_u32_e64 s[0:1], 0, v104
	v_cndmask_b32_e32 v14, v13, v14, vcc
	v_lshlrev_b32_e32 v112, 2, v14
	v_xor_b32_e32 v14, 2, v13
	v_cndmask_b32_e64 v121, 0, 1.0, s[0:1]
	v_cmp_eq_u32_e64 s[0:1], 1, v104
	s_add_i32 s8, 0, 0x1e400
	v_cmp_lt_i32_e32 vcc, v14, v15
	v_readlane_b32 s9, v238, 38
	v_cndmask_b32_e64 v122, 0, 1.0, s[0:1]
	v_cmp_eq_u32_e64 s[0:1], 2, v104
	s_lshl_b32 s2, s93, 3
	s_add_i32 s4, s54, s8
	v_cndmask_b32_e32 v14, v13, v14, vcc
	s_bfe_u32 s35, s9, 0x20006
	v_cndmask_b32_e64 v123, 0, 1.0, s[0:1]
	v_cmp_eq_u32_e64 s[0:1], 3, v104
	v_lshlrev_b32_e32 v113, 2, v14
	v_xor_b32_e32 v14, 4, v13
	s_cmpk_gt_u32 s9, 0xff
	v_cndmask_b32_e64 v124, 0, 1.0, s[0:1]
	v_cmp_eq_u32_e64 s[0:1], 4, v104
	v_cmp_lt_i32_e32 vcc, v14, v15
	s_cselect_b64 s[56:57], -1, 0
	s_cmpk_lt_u32 s9, 0x100
	v_cndmask_b32_e64 v125, 0, 1.0, s[0:1]
	v_cmp_eq_u32_e64 s[0:1], 5, v104
	v_cndmask_b32_e32 v13, v13, v14, vcc
	s_cselect_b64 vcc, -1, 0
	v_cndmask_b32_e64 v126, 0, 1.0, s[0:1]
	v_cmp_eq_u32_e64 s[0:1], 6, v104
	s_and_b64 s[6:7], vcc, exec
	s_mov_b32 s7, 0x16800
	v_cndmask_b32_e64 v127, 0, 1.0, s[0:1]
	v_cmp_eq_u32_e64 s[0:1], 7, v104
	s_cselect_b32 s34, s7, 0x18c00
	s_mov_b32 s7, 0x1b000
	v_cndmask_b32_e64 v128, 0, 1.0, s[0:1]
	v_cmp_eq_u32_e64 s[0:1], 8, v104
	s_cselect_b32 s6, 0, 0x2400
	s_cselect_b32 s10, s7, 0x12000
	v_cndmask_b32_e64 v129, 0, 1.0, s[0:1]
	v_cmp_eq_u32_e64 s[0:1], 9, v104
	s_mov_b32 s7, 0xfc00
	s_cselect_b32 s37, s7, 0x14400
	v_cndmask_b32_e64 v130, 0, 1.0, s[0:1]
	v_cmp_eq_u32_e64 s[0:1], 10, v104
	s_add_i32 s87, s6, 0
	s_lshr_b32 s94, s9, 7
	s_lshl_b32 s6, s93, 1
	v_cndmask_b32_e64 v131, 0, 1.0, s[0:1]
	v_cmp_eq_u32_e64 s[0:1], 11, v104
	s_and_b32 s95, s6, 2
	s_lshl_b32 s6, s94, 4
	v_cndmask_b32_e64 v132, 0, 1.0, s[0:1]
	v_cmp_eq_u32_e64 s[0:1], 12, v104
	v_lshrrev_b32_e32 v108, 4, v176
	v_or_b32_e32 v21, s6, v104
	s_movk_i32 s96, 0x90
	v_cndmask_b32_e64 v133, 0, 1.0, s[0:1]
	v_cmp_eq_u32_e64 s[0:1], 13, v104
	v_lshlrev_b32_e32 v105, 2, v108
	v_mul_lo_u32 v21, v21, s96
	v_cndmask_b32_e64 v134, 0, 1.0, s[0:1]
	v_cmp_eq_u32_e64 s[0:1], 14, v104
	s_lshl_b32 s36, s35, 4
	s_add_i32 s97, 0, 0x1d400
	v_add_u32_e32 v118, 0, v21
	v_or_b32_e32 v21, s6, v105
	s_add_i32 s6, s93, -2
	v_cndmask_b32_e64 v135, 0, 1.0, s[0:1]
	v_cmp_eq_u32_e64 s[0:1], 15, v104
	s_cmp_lt_u32 s6, 4
	s_cselect_b64 s[58:59], -1, 0
	v_cndmask_b32_e64 v136, 0, 1.0, s[0:1]
	s_mov_b32 s0, s93
	v_writelane_b32 v238, s0, 48
	s_lshl_b32 s0, s0, 10
	s_and_b32 s0, s0, 0x7ffff000
	v_or_b32_e32 v16, s36, v104
	v_lshlrev_b32_e32 v19, 2, v104
	s_lshl_b32 s38, s6, 10
	s_add_i32 s0, s0, 0
	v_add_u32_e32 v20, s97, v19
	v_and_b32_e32 v106, 48, v0
	v_lshl_add_u64 v[98:99], v[10:11], 0, s[54:55]
	s_add_i32 s97, s97, s38
	s_add_i32 s93, s34, 0
	s_add_i32 s0, s0, 0x23700
	v_lshlrev_b32_e32 v10, 6, v16
	v_lshrrev_b32_e32 v90, 3, v0
	v_mul_u32_u24_e32 v17, 0x48, v16
	v_add_u32_e32 v11, s0, v10
	v_add_u32_e32 v16, s0, v106
	s_cmp_eq_u32 s94, 2
	s_mov_b32 s0, 0x6400000
	v_lshlrev_b32_e32 v114, 2, v13
	v_mul_u32_u24_e32 v13, 0x104, v90
	v_lshlrev_b32_e32 v14, 5, v178
	s_cselect_b32 s0, s0, 0x1db00000
	s_cmp_lg_u32 s94, 1
	v_add3_u32 v115, s8, v13, v14
	v_add_u32_e32 v22, s8, v19
	s_cselect_b32 s8, s0, 0x4400000
	s_cmpk_gt_u32 s9, 0x7f
	s_cselect_b64 s[60:61], -1, 0
	s_and_b64 s[0:1], s[60:61], exec
	v_or_b32_e32 v18, s36, v105
	s_cselect_b32 s0, s8, 0x2400000
	s_add_u32 s66, s80, s0
	v_cmp_lt_u32_e64 s[0:1], v104, v18
	v_or_b32_e32 v34, 2, v18
	s_movk_i32 s85, 0x48
	v_cndmask_b32_e64 v29, 0, 1, s[0:1]
	v_cmp_le_u32_e64 s[0:1], v104, v18
	s_addc_u32 s67, s81, 0
	s_cmp_eq_u32 s35, 0
	v_cndmask_b32_e64 v30, 0, 1, s[0:1]
	v_cmp_lt_u32_e64 s[0:1], v104, v34
	s_cselect_b64 s[8:9], -1, 0
	s_and_b64 s[68:69], vcc, s[8:9]
	v_cndmask_b32_e64 v35, 0, 1, s[0:1]
	v_cmp_le_u32_e64 s[0:1], v104, v34
	s_add_i32 s42, s10, 0
	s_cmp_eq_u32 s35, 1
	v_cndmask_b32_e64 v36, 0, 1, s[0:1]
	v_cndmask_b32_e32 v35, v36, v35, vcc
	v_mov_b32_e32 v36, 0x90
	v_mad_u32_u24 v36, v18, s85, v36
	v_or_b32_e32 v37, v36, v104
	v_lshlrev_b32_e32 v142, 1, v37
	v_or_b32_e32 v37, 3, v18
	v_cmp_lt_u32_e64 s[0:1], v104, v37
	v_or_b32_e32 v144, 16, v104
	v_cndmask_b32_e32 v29, v30, v29, vcc
	v_cndmask_b32_e64 v38, 0, 1, s[0:1]
	v_cmp_le_u32_e64 s[0:1], v104, v37
	v_mul_u32_u24_e32 v30, 0x48, v18
	v_or_b32_e32 v31, v30, v104
	v_cndmask_b32_e64 v39, 0, 1, s[0:1]
	s_cselect_b64 s[0:1], -1, 0
	s_and_b64 s[70:71], vcc, s[0:1]
	v_cmp_lt_u32_e64 s[0:1], v144, v18
	s_cmp_eq_u32 s35, 2
	v_lshlrev_b32_e32 v140, 1, v31
	v_cndmask_b32_e64 v41, 0, 1, s[0:1]
	v_cmp_le_u32_e64 s[0:1], v144, v18
	v_or_b32_e32 v31, 1, v18
	v_cndmask_b32_e32 v38, v39, v38, vcc
	v_cndmask_b32_e64 v42, 0, 1, s[0:1]
	v_cndmask_b32_e32 v41, v42, v41, vcc
	v_or_b32_e32 v42, v30, v144
	v_cmp_lt_u32_e64 s[0:1], v144, v34
	v_lshlrev_b32_e32 v145, 1, v42
	v_mov_b32_e32 v39, 0xd8
	v_cndmask_b32_e64 v42, 0, 1, s[0:1]
	v_cmp_le_u32_e64 s[0:1], v144, v34
	v_cndmask_b32_e32 v32, v31, v18, vcc
	v_mad_u32_u24 v33, v18, s85, s85
	v_cndmask_b32_e64 v43, 0, 1, s[0:1]
	v_cndmask_b32_e32 v42, v43, v42, vcc
	v_and_b32_e32 v42, 1, v42
	v_cmp_lt_u32_e64 s[0:1], v144, v37
	v_cmp_eq_u32_e64 s[20:21], 1, v42
	v_mad_u32_u24 v39, v18, s85, v39
	v_cndmask_b32_e64 v42, 0, 1, s[0:1]
	v_cmp_le_u32_e64 s[0:1], v144, v37
	v_and_b32_e32 v41, 1, v41
	v_cmp_eq_u32_e64 s[16:17], 1, v41
	v_cndmask_b32_e64 v43, 0, 1, s[0:1]
	v_cndmask_b32_e32 v42, v43, v42, vcc
	v_and_b32_e32 v42, 1, v42
	v_cmp_eq_u32_e64 s[22:23], 1, v42
	v_or_b32_e32 v42, 32, v104
	s_cselect_b64 s[0:1], -1, 0
	s_and_b64 s[72:73], vcc, s[0:1]
	v_cmp_lt_u32_e64 s[0:1], v42, v18
	s_cmp_eq_u32 s35, 3
	v_add_lshl_u32 v150, v30, v42, 1
	v_cndmask_b32_e64 v44, 0, 1, s[0:1]
	v_cmp_le_u32_e64 s[0:1], v42, v18
	v_cmp_gt_u32_e64 s[26:27], v42, v32
	v_add_lshl_u32 v151, v33, v42, 1
	v_cndmask_b32_e64 v45, 0, 1, s[0:1]
	v_cndmask_b32_e32 v44, v45, v44, vcc
	v_and_b32_e32 v44, 1, v44
	v_cmp_lt_u32_e64 s[0:1], v42, v34
	v_cmp_eq_u32_e64 s[24:25], 1, v44
	v_add_lshl_u32 v152, v36, v42, 1
	v_cndmask_b32_e64 v44, 0, 1, s[0:1]
	v_cmp_le_u32_e64 s[0:1], v42, v34
	v_add_lshl_u32 v153, v39, v42, 1
	v_lshlrev_b32_e32 v41, 6, v18
	v_cndmask_b32_e64 v45, 0, 1, s[0:1]
	v_cndmask_b32_e32 v44, v45, v44, vcc
	v_and_b32_e32 v44, 1, v44
	v_cmp_lt_u32_e64 s[0:1], v42, v37
	v_cmp_eq_u32_e64 s[28:29], 1, v44
	v_add_lshl_u32 v141, v33, v104, 1
	v_cndmask_b32_e64 v44, 0, 1, s[0:1]
	v_cmp_le_u32_e64 s[0:1], v42, v37
	v_or_b32_e32 v42, 48, v104
	v_add_lshl_u32 v154, v30, v42, 1
	v_cndmask_b32_e64 v45, 0, 1, s[0:1]
	v_cndmask_b32_e32 v44, v45, v44, vcc
	s_cselect_b64 s[0:1], -1, 0
	v_and_b32_e32 v44, 1, v44
	s_and_b64 s[74:75], vcc, s[0:1]
	v_cmp_lt_u32_e64 s[0:1], v42, v18
	v_cmp_eq_u32_e64 s[30:31], 1, v44
	v_add_lshl_u32 v146, v33, v144, 1
	v_cndmask_b32_e64 v44, 0, 1, s[0:1]
	v_cmp_le_u32_e64 s[0:1], v42, v18
	v_add_lshl_u32 v155, v33, v42, 1
	v_and_b32_e32 v35, 1, v35
	v_cndmask_b32_e64 v18, 0, 1, s[0:1]
	v_cmp_lt_u32_e64 s[0:1], v42, v34
	v_cmp_eq_u32_e64 s[12:13], 1, v35
	v_lshlrev_b32_e32 v35, 6, v34
	v_cndmask_b32_e64 v30, 0, 1, s[0:1]
	v_cmp_le_u32_e64 s[0:1], v42, v34
	s_add_i32 s51, s38, 0
	v_add_lshl_u32 v143, v39, v104, 1
	v_cndmask_b32_e64 v33, 0, 1, s[0:1]
	v_cmp_lt_u32_e64 s[0:1], v42, v37
	v_cndmask_b32_e32 v30, v33, v30, vcc
	v_add_lshl_u32 v149, v39, v144, 1
	v_cndmask_b32_e64 v33, 0, 1, s[0:1]
	v_cmp_le_u32_e64 s[0:1], v42, v37
	v_cndmask_b32_e32 v18, v18, v44, vcc
	v_add_lshl_u32 v157, v39, v42, 1
	v_cndmask_b32_e64 v34, 0, 1, s[0:1]
	s_or_b32 s0, s95, 1
	v_lshl_add_u32 v39, s95, 6, v22
	v_lshl_or_b32 v44, s0, 4, v104
	v_lshl_add_u32 v22, s0, 6, v22
	s_add_i32 s0, s51, 0x22700
	v_writelane_b32 v238, s0, 39
	s_add_i32 s0, s51, 0x22740
	v_writelane_b32 v238, s0, 43
	s_add_i32 s0, s51, 0x22780
	v_writelane_b32 v238, s0, 49
	s_add_i32 s0, s51, 0x227c0
	v_writelane_b32 v238, s0, 50
	s_add_i32 s0, s51, 0x22800
	v_writelane_b32 v238, s0, 51
	s_add_i32 s0, s51, 0x22840
	v_writelane_b32 v238, s0, 52
	s_add_i32 s0, s51, 0x22880
	v_writelane_b32 v238, s0, 53
	s_add_i32 s0, s51, 0x228c0
	v_writelane_b32 v238, s0, 54
	s_add_i32 s0, s51, 0x22900
	v_writelane_b32 v238, s0, 55
	s_add_i32 s0, s51, 0x22940
	v_writelane_b32 v238, s0, 56
	s_add_i32 s0, s51, 0x22980
	v_writelane_b32 v238, s0, 57
	v_mul_u32_u24_e32 v47, 0x410, v108
	s_lshl_b32 s0, s35, 6
	v_add3_u32 v159, v47, s0, v19
	s_lshl_b32 s0, s35, 5
	s_mov_b32 s46, s40
	s_movk_i32 s40, 0x240
	v_mov_b32_e32 v19, s0
	v_lshlrev_b32_e32 v158, 1, v104
	v_mad_u32_u24 v19, v108, s40, v19
	v_add_u32_e32 v161, 0x16800, v1
	v_or_b32_e32 v1, v19, v158
	s_movk_i32 s39, 0x120
	v_add_u32_e32 v162, 0x90, v1
	v_mov_b32_e32 v1, s36
	v_lshrrev_b32_e32 v14, 6, v0
	v_mad_u32_u24 v1, v108, s39, v1
	v_bitop3_b32 v14, v14, v0, 7 bitop3:0x78
	v_lshlrev_b32_e32 v86, 3, v108
	v_or_b32_e32 v1, v1, v104
	v_lshlrev_b32_e32 v14, 3, v14
	v_bfe_u32 v15, v0, 3, 3
	v_lshlrev_b32_e32 v138, 6, v104
	v_mul_u32_u24_e32 v23, 0x240, v178
	v_cndmask_b32_e32 v33, v34, v33, vcc
	v_lshl_or_b32 v34, s95, 4, v104
	v_lshlrev_b32_e32 v163, 1, v1
	v_or_b32_e32 v1, s34, v86
	s_movk_i32 s33, 0x104
	v_mov_b32_e32 v12, s4
	v_or3_b32 v14, v14, v15, v23
	v_mul_u32_u24_e32 v107, 0x48, v104
	v_and_b32_e32 v38, 1, v38
	v_add_lshl_u32 v147, v36, v144, 1
	v_add_lshl_u32 v156, v36, v42, 1
	v_lshrrev_b32_e32 v36, 3, v34
	v_lshrrev_b32_e32 v45, 3, v44
	v_lshl_add_u32 v164, v17, 1, v1
	v_or_b32_e32 v1, v138, v106
	v_lshlrev_b32_e32 v110, 3, v178
	v_mad_u32_u24 v111, v176, s33, v12
	v_mul_u32_u24_e32 v12, 0xd0, v178
	v_mul_u32_u24_e32 v13, 0x48, v90
	v_lshlrev_b32_e32 v139, 1, v14
	v_add_lshl_u32 v28, v107, v86, 1
	v_and_b32_e32 v29, 1, v29
	v_cmp_eq_u32_e64 s[14:15], 1, v38
	v_lshlrev_b32_e32 v38, 6, v37
	v_xor_b32_e32 v37, v36, v108
	v_bitop3_b32 v36, v36, v108, 4 bitop3:0x1e
	v_xor_b32_e32 v46, v45, v108
	v_bitop3_b32 v45, v45, v108, 4 bitop3:0x1e
	v_add_u32_e32 v165, 0x22700, v1
	v_and_b32_e32 v1, 48, v176
	v_add_lshl_u32 v13, v13, v110, 1
	v_or_b32_e32 v119, 4, v108
	v_add_u32_e32 v14, 0x90, v139
	v_add_u32_e32 v15, 0x120, v139
	v_add_u32_e32 v23, 0x1b0, v139
	v_add_u32_e32 v24, 0x240, v139
	v_add_u32_e32 v25, 0x2d0, v139
	v_add_u32_e32 v26, 0x360, v139
	v_add_u32_e32 v27, 0x3f0, v139
	v_add_u32_e32 v148, 0, v28
	v_cmp_eq_u32_e64 s[8:9], 1, v29
	v_lshlrev_b32_e32 v29, 8, v108
	v_lshlrev_b32_e32 v31, 6, v31
	v_add_u32_e32 v40, 0x900, v28
	v_add_u32_e32 v43, 0x1200, v28
	v_add_u32_e32 v28, 0x1b00, v28
	v_and_b32_e32 v18, 1, v18
	v_and_b32_e32 v30, 1, v30
	v_and_b32_e32 v33, 1, v33
	v_mad_u32_u24 v34, v34, s96, 0
	v_lshlrev_b32_e32 v37, 4, v37
	v_lshlrev_b32_e32 v36, 4, v36
	v_mul_lo_u32 v21, v21, s33
	v_mad_u32_u24 v44, v44, s96, 0
	v_lshlrev_b32_e32 v46, 4, v46
	v_lshlrev_b32_e32 v45, 4, v45
	s_mov_b32 s0, s46
	v_mad_u32_u24 v166, v104, s96, v1
	v_add_u32_e32 v1, 0, v12
	v_mov_b32_e32 v91, v89
	v_mov_b32_e32 v93, s53
	v_cmp_eq_u32_e64 s[44:45], 63, v176
	v_cmp_lt_u32_e64 s[4:5], 7, v0
	v_add_u32_e32 v116, 0xfffffefc, v115
	v_add_lshl_u32 v117, v17, v86, 1
	v_lshlrev_b32_e32 v120, 4, v119
	v_cmp_gt_u32_e64 s[6:7], 16, v176
	v_bfe_u32 v137, v176, 4, 1
	v_and_b32_e32 v87, 8, v105
	v_cmp_gt_u32_e64 s[10:11], v104, v32
	v_cmp_gt_u32_e64 s[18:19], v144, v32
	s_add_i32 s43, s37, 0
	s_add_i32 s92, s51, 0x229c0
	s_add_i32 s86, s51, 0x22a00
	s_add_i32 s33, s51, 0x22a40
	s_add_i32 s50, s51, 0x22a80
	s_add_i32 s51, s51, 0x22ac0
	v_writelane_b32 v238, s0, 58
	s_and_b32 s84, s46, 3
	v_or_b32_e32 v160, 0xfffffe00, v0
	s_movk_i32 s64, 0xe40
	s_lshl_b32 s65, s2, 2
	v_add_u32_e32 v167, 0x25700, v1
	v_mov_b32_e32 v168, 0x260
	v_add_u32_e32 v169, 0, v13
	v_add_u32_e32 v170, 0, v14
	v_add_u32_e32 v171, 0, v15
	v_add_u32_e32 v172, 0, v23
	v_add_u32_e32 v173, 0, v24
	v_add_u32_e32 v174, 0, v25
	v_add_u32_e32 v175, 0, v26
	v_add_u32_e32 v177, 0, v27
	v_add_u32_e32 v178, v20, v29
	v_add_u32_e32 v179, v34, v37
	v_add_u32_e32 v180, v34, v36
	v_add_u32_e32 v181, v39, v21
	v_add_u32_e32 v182, v44, v46
	v_add_u32_e32 v183, v44, v45
	v_add_u32_e32 v184, v22, v21
	v_add_u32_e32 v185, v11, v86
	v_add_u32_e32 v186, v16, v10
	v_mov_b32_e32 v10, v89
	v_mov_b32_e32 v11, v89
	v_mov_b32_e32 v12, v89
	v_mov_b32_e32 v13, v89
	v_add_u32_e32 v187, v20, v31
	v_add_u32_e32 v188, v20, v35
	v_add_u32_e32 v189, v20, v38
	v_add_u32_e32 v190, 0, v40
	v_add_u32_e32 v191, v20, v41
	v_add_u32_e32 v192, 0, v43
	v_add_u32_e32 v193, 0, v28
	s_mov_b32 s46, 0
	v_cmp_eq_u32_e64 s[34:35], 1, v18
	v_cmp_gt_u32_e64 s[36:37], v42, v32
	v_cmp_eq_u32_e64 s[38:39], 1, v30
	v_cmp_eq_u32_e64 s[40:41], 1, v33
	v_writelane_b32 v238, s1, 59
	s_lshl_b32 s98, s84, 6
	s_or_b32 s98, s52, s98
	s_mov_b32 s99, s53
	v_lshl_add_u64 v[228:229], s[98:99], 0, v[90:91]
	v_mad_u64_u32 v[230:231], s[98:99], v228, s64, v[94:95]
	v_mad_i32_i24 v231, v229, s64, v231
	v_lshlrev_b64 v[228:229], 10, v[228:229]
	v_lshl_add_u64 v[232:233], v[96:97], 0, v[228:229]
	global_load_dwordx4 v[200:203], v[230:231], off
	global_load_dwordx4 v[204:207], v[230:231], off offset:1024
	global_load_dwordx4 v[208:211], v[230:231], off offset:2048
	v_or_b32_e32 v234, s84, v90
	v_cmp_ne_u32_e32 vcc, 0, v234
	v_mov_b32_e32 v212, v89
	v_mov_b32_e32 v213, v89
	v_mov_b32_e32 v214, v89
	v_mov_b32_e32 v215, v89
	v_mov_b32_e32 v216, v89
	v_mov_b32_e32 v217, v89
	v_mov_b32_e32 v218, v89
	v_mov_b32_e32 v219, v89
	v_mov_b32_e32 v220, v89
	v_mov_b32_e32 v221, v89
	v_mov_b32_e32 v222, v89
	v_mov_b32_e32 v223, v89
	s_and_saveexec_b64 s[98:99], vcc
	s_cbranch_execz .Lrc_p0
	global_load_dwordx4 v[212:215], v[230:231], off offset:-3648
	global_load_dwordx4 v[216:219], v[230:231], off offset:-2624
	global_load_dwordx4 v[220:223], v[230:231], off offset:-1600
.Lrc_p0:
	s_or_b64 exec, exec, s[98:99]
	global_load_dwordx4 v[224:227], v[232:233], off
	s_branch .LBB0_1035

.LBB0_1035:
	s_lshl_b32 s0, s46, 2
	s_or_b32 s76, s84, s0
	s_lshl_b32 s54, s76, 6
	s_or_b32 s0, s52, s54
	s_mov_b32 s1, s53
	v_lshl_add_u64 v[22:23], s[0:1], 0, v[90:91]
	v_lshlrev_b64 v[22:23], 10, v[22:23]
	v_lshl_add_u64 v[102:103], v[96:97], 0, v[22:23]
	s_cmp_lg_u32 s46, 0
	s_cbranch_scc1 .Lrc_hw
	s_waitcnt vmcnt(0)
.Lrc_hw:
	s_waitcnt vmcnt(4)
	v_mov_b64_e32 v[30:31], v[200:201]
	v_mov_b64_e32 v[32:33], v[202:203]
	v_mov_b64_e32 v[26:27], v[204:205]
	v_mov_b64_e32 v[28:29], v[206:207]
	v_mov_b64_e32 v[14:15], v[208:209]
	v_mov_b64_e32 v[16:17], v[210:211]
	v_mov_b64_e32 v[38:39], v[212:213]
	v_mov_b64_e32 v[40:41], v[214:215]
	v_mov_b64_e32 v[34:35], v[216:217]
	v_mov_b64_e32 v[36:37], v[218:219]
	v_mov_b64_e32 v[18:19], v[220:221]
	v_mov_b64_e32 v[20:21], v[222:223]
	v_mov_b64_e32 v[42:43], v[224:225]
	v_mov_b64_e32 v[44:45], v[226:227]
	v_add_f32_dpp v1, v6, v6 row_shr:1 row_mask:0xf bank_mask:0xf bound_ctrl:1
	s_lshl_b32 s0, s46, 8
	v_mov_b32_e32 v22, v89
	v_add_f32_dpp v1, v1, v1 row_shr:2 row_mask:0xf bank_mask:0xf bound_ctrl:1
	s_and_b32 s0, s0, 0x100
	s_add_i32 s47, s0, 0
	v_add_f32_dpp v1, v1, v1 row_shr:4 row_mask:0xf bank_mask:0xf bound_ctrl:1
	s_add_i32 s47, s47, 0x22500
	s_add_i32 s2, s47, s65
	v_add_f32_dpp v1, v1, v1 row_shr:8 row_mask:0xf bank_mask:0xf bound_ctrl:1
	s_nop 1
	v_mov_b32_dpp v22, v1 row_bcast:15 row_mask:0xa bank_mask:0xf
	v_add_f32_e32 v1, v1, v22
	v_mov_b32_e32 v22, v89
	s_nop 1
	v_mov_b32_dpp v22, v1 row_bcast:31 row_mask:0xc bank_mask:0xf
	v_add_f32_e32 v1, v1, v22
	ds_write_b32 v111, v1
	s_and_saveexec_b64 s[0:1], s[44:45]
	v_mov_b32_e32 v22, s2
	ds_write_b32 v22, v1
	s_or_b64 exec, exec, s[0:1]
	v_add_f32_dpp v1, v7, v7 row_shr:1 row_mask:0xf bank_mask:0xf bound_ctrl:1
	v_mov_b32_e32 v22, v89
	s_nop 0
	v_add_f32_dpp v1, v1, v1 row_shr:2 row_mask:0xf bank_mask:0xf bound_ctrl:1
	s_nop 1
	v_add_f32_dpp v1, v1, v1 row_shr:4 row_mask:0xf bank_mask:0xf bound_ctrl:1
	s_nop 1
	v_add_f32_dpp v1, v1, v1 row_shr:8 row_mask:0xf bank_mask:0xf bound_ctrl:1
	s_nop 1
	v_mov_b32_dpp v22, v1 row_bcast:15 row_mask:0xa bank_mask:0xf
	v_add_f32_e32 v1, v1, v22
	v_mov_b32_e32 v22, v89
	s_nop 1
	v_mov_b32_dpp v22, v1 row_bcast:31 row_mask:0xc bank_mask:0xf
	v_add_f32_e32 v1, v1, v22
	ds_write_b32 v111, v1 offset:4
	s_and_saveexec_b64 s[0:1], s[44:45]
	v_mov_b32_e32 v22, s2
	ds_write_b32 v22, v1 offset:4
	s_or_b64 exec, exec, s[0:1]
	v_add_f32_dpp v1, v8, v8 row_shr:1 row_mask:0xf bank_mask:0xf bound_ctrl:1
	v_mov_b32_e32 v22, v89
	s_nop 0
	v_add_f32_dpp v1, v1, v1 row_shr:2 row_mask:0xf bank_mask:0xf bound_ctrl:1
	s_nop 1
	v_add_f32_dpp v1, v1, v1 row_shr:4 row_mask:0xf bank_mask:0xf bound_ctrl:1
	s_nop 1
	v_add_f32_dpp v1, v1, v1 row_shr:8 row_mask:0xf bank_mask:0xf bound_ctrl:1
	s_nop 1
	v_mov_b32_dpp v22, v1 row_bcast:15 row_mask:0xa bank_mask:0xf
	v_add_f32_e32 v1, v1, v22
	v_mov_b32_e32 v22, v89
	s_nop 1
	v_mov_b32_dpp v22, v1 row_bcast:31 row_mask:0xc bank_mask:0xf
	v_add_f32_e32 v1, v1, v22
	ds_write_b32 v111, v1 offset:8
	s_and_saveexec_b64 s[0:1], s[44:45]
	v_mov_b32_e32 v22, s2
	ds_write_b32 v22, v1 offset:8
	s_or_b64 exec, exec, s[0:1]
	v_add_f32_dpp v1, v9, v9 row_shr:1 row_mask:0xf bank_mask:0xf bound_ctrl:1
	v_mov_b32_e32 v22, v89
	s_nop 0
	v_add_f32_dpp v1, v1, v1 row_shr:2 row_mask:0xf bank_mask:0xf bound_ctrl:1
	s_nop 1
	v_add_f32_dpp v1, v1, v1 row_shr:4 row_mask:0xf bank_mask:0xf bound_ctrl:1
	s_nop 1
	v_add_f32_dpp v1, v1, v1 row_shr:8 row_mask:0xf bank_mask:0xf bound_ctrl:1
	s_nop 1
	v_mov_b32_dpp v22, v1 row_bcast:15 row_mask:0xa bank_mask:0xf
	v_add_f32_e32 v1, v1, v22
	v_mov_b32_e32 v22, v89
	s_nop 1
	v_mov_b32_dpp v22, v1 row_bcast:31 row_mask:0xc bank_mask:0xf
	v_add_f32_e32 v1, v1, v22
	ds_write_b32 v111, v1 offset:12
	s_and_saveexec_b64 s[0:1], s[44:45]
	v_mov_b32_e32 v22, s2
	ds_write_b32 v22, v1 offset:12
	s_or_b64 exec, exec, s[0:1]
	v_add_f32_dpp v1, v2, v2 row_shr:1 row_mask:0xf bank_mask:0xf bound_ctrl:1
	v_mov_b32_e32 v22, v89
	s_nop 0
	v_add_f32_dpp v1, v1, v1 row_shr:2 row_mask:0xf bank_mask:0xf bound_ctrl:1
	s_nop 1
	v_add_f32_dpp v1, v1, v1 row_shr:4 row_mask:0xf bank_mask:0xf bound_ctrl:1
	s_nop 1
	v_add_f32_dpp v1, v1, v1 row_shr:8 row_mask:0xf bank_mask:0xf bound_ctrl:1
	s_nop 1
	v_mov_b32_dpp v22, v1 row_bcast:15 row_mask:0xa bank_mask:0xf
	v_add_f32_e32 v1, v1, v22
	v_mov_b32_e32 v22, v89
	s_nop 1
	v_mov_b32_dpp v22, v1 row_bcast:31 row_mask:0xc bank_mask:0xf
	v_add_f32_e32 v1, v1, v22
	ds_write_b32 v111, v1 offset:16
	s_and_saveexec_b64 s[0:1], s[44:45]
	v_mov_b32_e32 v22, s2
	ds_write_b32 v22, v1 offset:16
	s_or_b64 exec, exec, s[0:1]
	v_add_f32_dpp v1, v3, v3 row_shr:1 row_mask:0xf bank_mask:0xf bound_ctrl:1
	v_mov_b32_e32 v22, v89
	s_nop 0
	v_add_f32_dpp v1, v1, v1 row_shr:2 row_mask:0xf bank_mask:0xf bound_ctrl:1
	s_nop 1
	v_add_f32_dpp v1, v1, v1 row_shr:4 row_mask:0xf bank_mask:0xf bound_ctrl:1
	s_nop 1
	v_add_f32_dpp v1, v1, v1 row_shr:8 row_mask:0xf bank_mask:0xf bound_ctrl:1
	s_nop 1
	v_mov_b32_dpp v22, v1 row_bcast:15 row_mask:0xa bank_mask:0xf
	v_add_f32_e32 v1, v1, v22
	v_mov_b32_e32 v22, v89
	s_nop 1
	v_mov_b32_dpp v22, v1 row_bcast:31 row_mask:0xc bank_mask:0xf
	v_add_f32_e32 v1, v1, v22
	ds_write_b32 v111, v1 offset:20
	s_and_saveexec_b64 s[0:1], s[44:45]
	v_mov_b32_e32 v22, s2
	ds_write_b32 v22, v1 offset:20
	s_or_b64 exec, exec, s[0:1]
	v_add_f32_dpp v1, v4, v4 row_shr:1 row_mask:0xf bank_mask:0xf bound_ctrl:1
	v_mov_b32_e32 v22, v89
	s_nop 0
	v_add_f32_dpp v1, v1, v1 row_shr:2 row_mask:0xf bank_mask:0xf bound_ctrl:1
	s_nop 1
	v_add_f32_dpp v1, v1, v1 row_shr:4 row_mask:0xf bank_mask:0xf bound_ctrl:1
	s_nop 1
	v_add_f32_dpp v1, v1, v1 row_shr:8 row_mask:0xf bank_mask:0xf bound_ctrl:1
	s_nop 1
	v_mov_b32_dpp v22, v1 row_bcast:15 row_mask:0xa bank_mask:0xf
	v_add_f32_e32 v1, v1, v22
	v_mov_b32_e32 v22, v89
	s_nop 1
	v_mov_b32_dpp v22, v1 row_bcast:31 row_mask:0xc bank_mask:0xf
	v_add_f32_e32 v1, v1, v22
	ds_write_b32 v111, v1 offset:24
	s_and_saveexec_b64 s[0:1], s[44:45]
	v_mov_b32_e32 v22, s2
	ds_write_b32 v22, v1 offset:24
	s_or_b64 exec, exec, s[0:1]
	v_add_f32_dpp v1, v5, v5 row_shr:1 row_mask:0xf bank_mask:0xf bound_ctrl:1
	v_mov_b32_e32 v22, v89
	s_nop 0
	v_add_f32_dpp v1, v1, v1 row_shr:2 row_mask:0xf bank_mask:0xf bound_ctrl:1
	s_nop 1
	v_add_f32_dpp v1, v1, v1 row_shr:4 row_mask:0xf bank_mask:0xf bound_ctrl:1
	s_nop 1
	v_add_f32_dpp v1, v1, v1 row_shr:8 row_mask:0xf bank_mask:0xf bound_ctrl:1
	s_nop 1
	v_mov_b32_dpp v22, v1 row_bcast:15 row_mask:0xa bank_mask:0xf
	v_add_f32_e32 v1, v1, v22
	v_mov_b32_e32 v22, v89
	s_nop 1
	v_mov_b32_dpp v22, v1 row_bcast:31 row_mask:0xc bank_mask:0xf
	v_add_f32_e32 v1, v1, v22
	ds_write_b32 v111, v1 offset:28
	s_and_saveexec_b64 s[0:1], s[44:45]
	v_mov_b32_e32 v22, s2
	ds_write_b32 v22, v1 offset:28
	s_or_b64 exec, exec, s[0:1]
	s_waitcnt vmcnt(3)
	v_and_b32_e32 v195, 0xffff0000, v30
	v_lshlrev_b32_e32 v194, 16, v30
	v_and_b32_e32 v199, 0xffff0000, v38
	v_lshlrev_b32_e32 v198, 16, v38
	s_waitcnt lgkmcnt(0)
	s_barrier
	ds_read_b128 v[82:85], v167
	ds_read_b128 v[54:57], v167 offset:16
	ds_read_b128 v[70:73], v167 offset:32
	ds_read_b128 v[50:53], v167 offset:48
	ds_read_b128 v[22:25], v167 offset:64
	ds_read_b128 v[78:81], v167 offset:96
	ds_read_b128 v[46:49], v167 offset:112
	ds_read_b128 v[74:77], v167 offset:128
	ds_read_b128 v[62:65], v167 offset:144
	ds_read_b128 v[66:69], v167 offset:160
	ds_read_b128 v[58:61], v167 offset:176
	v_pk_add_f32 v[198:199], v[198:199], v[194:195] neg_lo:[0,1] neg_hi:[0,1]
	s_waitcnt vmcnt(2)
	v_and_b32_e32 v197, 0xffff0000, v26
	v_lshlrev_b32_e32 v196, 16, v26
	s_waitcnt lgkmcnt(10)
	v_pk_fma_f32 v[82:83], v[198:199], v[82:83], v[194:195]
	v_and_b32_e32 v195, 0xffff0000, v34
	v_lshlrev_b32_e32 v194, 16, v34
	s_waitcnt vmcnt(0)
	v_and_b32_e32 v101, 0xffff0000, v42
	v_lshlrev_b32_e32 v100, 16, v42
	v_pk_add_f32 v[194:195], v[194:195], v[196:197] neg_lo:[0,1] neg_hi:[0,1]
	v_lshlrev_b32_e32 v30, 16, v27
	s_waitcnt lgkmcnt(8)
	v_pk_fma_f32 v[70:71], v[194:195], v[70:71], v[196:197]
	v_pk_add_f32 v[194:195], v[100:101], -1.0 op_sel_hi:[1,0]
	s_waitcnt lgkmcnt(5)
	v_mul_f32_e32 v78, v70, v78
	s_waitcnt lgkmcnt(3)
	v_pk_fma_f32 v[74:75], v[194:195], v[74:75], 1.0 op_sel_hi:[1,1,0]
	v_mul_f32_e32 v1, v71, v79
	v_pk_mul_f32 v[70:71], v[70:71], v[74:75]
	v_mul_f32_e32 v79, v1, v1
	v_pk_mul_f32 v[74:75], v[82:83], v[70:71]
	v_fmac_f32_e32 v79, v78, v78
	s_waitcnt lgkmcnt(1)
	v_pk_mul_f32 v[66:67], v[66:67], v[74:75]
	v_and_b32_e32 v75, 0xffff0000, v31
	v_add_f32_e32 v26, 0, v66
	v_add_f32_e32 v42, v67, v26
	v_lshlrev_b32_e32 v74, 16, v31
	v_and_b32_e32 v31, 0xffff0000, v27
	v_and_b32_e32 v27, 0xffff0000, v39
	v_lshlrev_b32_e32 v26, 16, v39
	v_pk_add_f32 v[26:27], v[26:27], v[74:75] neg_lo:[0,1] neg_hi:[0,1]
	v_and_b32_e32 v67, 0xffff0000, v43
	v_pk_fma_f32 v[38:39], v[26:27], v[84:85], v[74:75]
	v_and_b32_e32 v27, 0xffff0000, v35
	v_lshlrev_b32_e32 v26, 16, v35
	v_lshlrev_b32_e32 v66, 16, v43
	v_pk_add_f32 v[26:27], v[26:27], v[30:31] neg_lo:[0,1] neg_hi:[0,1]
	v_and_b32_e32 v43, 0xffff0000, v40
	v_pk_fma_f32 v[26:27], v[26:27], v[72:73], v[30:31]
	v_pk_add_f32 v[30:31], v[66:67], -1.0 op_sel_hi:[1,0]
	v_mul_f32_e32 v73, v26, v80
	v_pk_fma_f32 v[30:31], v[30:31], v[76:77], 1.0 op_sel_hi:[1,1,0]
	v_mul_f32_e32 v72, v27, v81
	v_pk_mul_f32 v[34:35], v[26:27], v[30:31]
	v_and_b32_e32 v31, 0xffff0000, v28
	v_pk_mul_f32 v[26:27], v[38:39], v[34:35]
	v_lshlrev_b32_e32 v30, 16, v28
	v_pk_mul_f32 v[26:27], v[68:69], v[26:27]
	v_and_b32_e32 v69, 0xffff0000, v44
	v_add_f32_e32 v26, v26, v42
	v_add_f32_e32 v74, v27, v26
	v_and_b32_e32 v27, 0xffff0000, v32
	v_lshlrev_b32_e32 v26, 16, v32
	v_lshlrev_b32_e32 v42, 16, v40
	v_pk_add_f32 v[42:43], v[42:43], v[26:27] neg_lo:[0,1] neg_hi:[0,1]
	v_lshlrev_b32_e32 v68, 16, v44
	v_pk_fma_f32 v[54:55], v[42:43], v[54:55], v[26:27]
	v_and_b32_e32 v27, 0xffff0000, v36
	v_lshlrev_b32_e32 v26, 16, v36
	v_pk_add_f32 v[26:27], v[26:27], v[30:31] neg_lo:[0,1] neg_hi:[0,1]
	v_lshlrev_b32_e32 v32, 16, v29
	v_pk_fma_f32 v[26:27], v[26:27], v[50:51], v[30:31]
	v_pk_add_f32 v[30:31], v[68:69], -1.0 op_sel_hi:[1,0]
	v_mul_f32_e32 v44, v26, v46
	v_pk_fma_f32 v[30:31], v[30:31], v[62:63], 1.0 op_sel_hi:[1,1,0]
	v_mul_f32_e32 v40, v27, v47
	v_pk_mul_f32 v[42:43], v[26:27], v[30:31]
	v_lshlrev_b32_e32 v28, 16, v41
	v_pk_mul_f32 v[26:27], v[54:55], v[42:43]
	v_and_b32_e32 v31, 0xffff0000, v45
	s_waitcnt lgkmcnt(0)
	v_pk_mul_f32 v[26:27], v[58:59], v[26:27]
	v_lshlrev_b32_e32 v30, 16, v45
	v_add_f32_e32 v26, v26, v74
	v_add_f32_e32 v36, v27, v26
	v_and_b32_e32 v27, 0xffff0000, v33
	v_lshlrev_b32_e32 v26, 16, v33
	v_and_b32_e32 v33, 0xffff0000, v29
	v_and_b32_e32 v29, 0xffff0000, v41
	v_pk_add_f32 v[28:29], v[28:29], v[26:27] neg_lo:[0,1] neg_hi:[0,1]
	v_fmac_f32_e32 v79, v73, v73
	v_pk_fma_f32 v[26:27], v[28:29], v[56:57], v[26:27]
	v_and_b32_e32 v29, 0xffff0000, v37
	v_lshlrev_b32_e32 v28, 16, v37
	v_pk_add_f32 v[28:29], v[28:29], v[32:33] neg_lo:[0,1] neg_hi:[0,1]
	v_fmac_f32_e32 v79, v72, v72
	v_pk_fma_f32 v[32:33], v[28:29], v[52:53], v[32:33]
	v_pk_add_f32 v[28:29], v[30:31], -1.0 op_sel_hi:[1,0]
	v_mul_f32_e32 v37, v32, v48
	v_pk_fma_f32 v[28:29], v[28:29], v[64:65], 1.0 op_sel_hi:[1,1,0]
	v_fmac_f32_e32 v79, v44, v44
	v_pk_mul_f32 v[28:29], v[32:33], v[28:29]
	v_fmac_f32_e32 v79, v40, v40
	v_pk_mul_f32 v[46:47], v[26:27], v[28:29]
	v_fmac_f32_e32 v79, v37, v37
	v_pk_mul_f32 v[46:47], v[60:61], v[46:47]
	v_lshl_add_u32 v88, v110, 2, s47
	v_add_f32_e32 v32, v46, v36
	v_add_f32_e32 v32, v47, v32
	ds_bpermute_b32 v41, v112, v32
	v_mul_f32_e32 v36, v33, v49
	v_fmac_f32_e32 v79, v36, v36
	ds_bpermute_b32 v33, v112, v79
	v_lshlrev_b32_e32 v58, 16, v18
	s_waitcnt lgkmcnt(1)
	v_add_f32_e32 v32, v32, v41
	ds_bpermute_b32 v45, v113, v32
	ds_read_b32 v41, v88
	ds_read_b128 v[48:51], v167 offset:80
	s_waitcnt lgkmcnt(3)
	v_add_f32_e32 v33, v79, v33
	ds_bpermute_b32 v47, v113, v33
	v_and_b32_e32 v59, 0xffff0000, v18
	s_waitcnt lgkmcnt(3)
	v_add_f32_e32 v32, v32, v45
	ds_bpermute_b32 v52, v114, v32
	v_lshlrev_b32_e32 v18, 16, v19
	s_waitcnt lgkmcnt(1)
	v_add_f32_e32 v53, v33, v47
	v_and_b32_e32 v33, 0xffff0000, v14
	v_and_b32_e32 v19, 0xffff0000, v19
	s_waitcnt lgkmcnt(0)
	v_add_f32_e32 v52, v32, v52
	v_lshlrev_b32_e32 v32, 16, v14
	v_lshlrev_b32_e32 v14, 16, v15
	v_and_b32_e32 v15, 0xffff0000, v15
	v_pk_add_f32 v[58:59], v[58:59], v[32:33] neg_lo:[0,1] neg_hi:[0,1]
	v_pk_add_f32 v[18:19], v[18:19], v[14:15] neg_lo:[0,1] neg_hi:[0,1]
	v_pk_fma_f32 v[32:33], v[58:59], v[22:23], v[32:33]
	v_pk_fma_f32 v[22:23], v[18:19], v[24:25], v[14:15]
	v_lshlrev_b32_e32 v14, 16, v16
	v_and_b32_e32 v15, 0xffff0000, v16
	v_lshlrev_b32_e32 v18, 16, v20
	v_and_b32_e32 v19, 0xffff0000, v20
	v_pk_add_f32 v[18:19], v[18:19], v[14:15] neg_lo:[0,1] neg_hi:[0,1]
	ds_read_b32 v45, v115
	ds_bpermute_b32 v56, v114, v53
	v_pk_fma_f32 v[18:19], v[18:19], v[48:49], v[14:15]
	v_lshlrev_b32_e32 v14, 16, v17
	v_and_b32_e32 v15, 0xffff0000, v17
	v_lshlrev_b32_e32 v16, 16, v21
	v_and_b32_e32 v17, 0xffff0000, v21
	v_pk_add_f32 v[16:17], v[16:17], v[14:15] neg_lo:[0,1] neg_hi:[0,1]
	v_pk_mul_f32 v[58:59], v[32:33], v[52:53] op_sel_hi:[1,0]
	v_pk_fma_f32 v[14:15], v[16:17], v[50:51], v[14:15]
	v_pk_mul_f32 v[24:25], v[22:23], v[52:53] op_sel_hi:[1,0]
	v_pk_mul_f32 v[60:61], v[18:19], v[52:53] op_sel_hi:[1,0]
	v_pk_mul_f32 v[16:17], v[14:15], v[52:53] op_sel_hi:[1,0]
	v_mov_b32_e32 v46, 0
	v_cvt_pk_bf16_f32 v48, v58, v59
	v_cvt_pk_bf16_f32 v49, v24, v25
	v_cvt_pk_bf16_f32 v50, v60, v61
	v_cvt_pk_bf16_f32 v51, v16, v17
	v_mov_b32_e32 v20, 0
	global_store_dwordx4 v[102:103], v[48:51], off
	s_and_saveexec_b64 s[0:1], s[4:5]
	s_cbranch_execz .LBB0_1055
	ds_read_b32 v16, v116
	s_waitcnt lgkmcnt(0)
	v_mul_f32_e32 v20, 0x3fb8aa3b, v16

.LBB0_1107:
	s_mov_b32 s2, 4
	v_mov_b32_e32 v1, v166
	v_mov_b32_e32 v22, v165
	v_mov_b32_e32 v23, v164
	v_mov_b32_e32 v24, v163
	v_mov_b32_e32 v25, v162
	v_mov_b32_e32 v26, v159
	s_waitcnt lgkmcnt(0)
	s_barrier
	s_cmp_eq_u32 s46, 15
	s_cbranch_scc1 .Lrc_nopf
	s_add_i32 s98, s46, 1
	s_lshl_b32 s98, s98, 2
	s_or_b32 s98, s84, s98
	s_lshl_b32 s98, s98, 6
	s_or_b32 s98, s52, s98
	s_mov_b32 s99, s53
	v_lshl_add_u64 v[228:229], s[98:99], 0, v[90:91]
	v_mad_u64_u32 v[230:231], s[98:99], v228, s64, v[94:95]
	v_mad_i32_i24 v231, v229, s64, v231
	v_lshlrev_b64 v[228:229], 10, v[228:229]
	v_lshl_add_u64 v[232:233], v[96:97], 0, v[228:229]
	global_load_dwordx4 v[200:203], v[230:231], off
	global_load_dwordx4 v[204:207], v[230:231], off offset:1024
	global_load_dwordx4 v[208:211], v[230:231], off offset:2048
	global_load_dwordx4 v[212:215], v[230:231], off offset:-3648
	global_load_dwordx4 v[216:219], v[230:231], off offset:-2624
	global_load_dwordx4 v[220:223], v[230:231], off offset:-1600
	global_load_dwordx4 v[224:227], v[232:233], off
.Lrc_nopf:
	s_branch .LBB0_1109
.LBB0_1108:
	s_waitcnt lgkmcnt(2)
	s_nop 3
	v_pk_add_f32 v[14:15], v[18:19], v[14:15] op_sel:[1,0] op_sel_hi:[0,1] neg_lo:[0,1] neg_hi:[0,1]
	s_waitcnt lgkmcnt(0)
	v_pk_add_f32 v[16:17], v[20:21], v[16:17] op_sel:[1,0] op_sel_hi:[0,1] neg_lo:[0,1] neg_hi:[0,1]
	v_cvt_pk_bf16_f32 v14, v14, v15
	v_cvt_pk_bf16_f32 v15, v16, v17
	ds_write_b64 v185, v[14:15]
	s_waitcnt lgkmcnt(0)
	v_add_u32_e32 v14, 0, v22
	ds_read_b128 v[14:17], v14
	ds_read_b128 v[18:21], v186
	s_add_i32 s2, s2, -1
	s_waitcnt lgkmcnt(0)
	v_mfma_f32_16x16x32_bf16 v[14:17], v[14:17], v[18:21], 0
	v_add_u32_e32 v26, 0x1040, v26
	v_add_u32_e32 v25, 0x900, v25
	v_add_u32_e32 v24, 0x900, v24
	s_nop 4
	v_cvt_pk_bf16_f32 v14, v14, v15
	v_cvt_pk_bf16_f32 v15, v16, v17
	v_add_u32_e32 v16, 0, v23
	ds_write_b64 v16, v[14:15]
	s_waitcnt lgkmcnt(0)
	v_add_u32_e32 v23, 32, v23
	v_add_u32_e32 v22, 0x400, v22
	v_add_u32_e32 v1, 0x900, v1
	s_cmp_eq_u32 s2, 0
	s_cbranch_scc1 .LBB0_1113
